# MLA tile loop unrolled by 2 (one body per LDS buffer): the 4 per-tile LDS address adds and the buffer-offset scalar math are gone
# speedup vs baseline: 1.0048x; 1.0048x over previous
; #define LAS __attribute__((address_space(3)))
; template <bool MLA> __device__ __forceinline__ void attn_unit(const AttnP& P, int b, int hh, int qb, LAS char* lds) {
;     ...
;     const int tid = threadIdx.x, wid = __builtin_amdgcn_readfirstlane(tid >> 6), lane = tid & 63, r32 = lane & 31, hi = lane >> 5;
;     LAS char* V_lds = lds; LAS char* K_lds = lds + 2 * VBYTES;
;     LAS float* ws = (LAS float*)(lds + 2 * VBYTES + 2 * KBYTES) + wid * 64; LAS float* li_l = ws; LAS float* al_l = ws + 32;
;     LAS float* bias_l = (LAS float*)(lds + 2 * VBYTES + 2 * KBYTES + 2048);
;     const int q0 = qb * 256; const size_t rowbase = (size_t)b * SEQ;
;     const int jt0 = MLA ? 0 : (q0 == 0 ? 0 : -2);
;     const int NT = MLA ? 4 * qb + 4 : 4 - jt0;
;     const int kbase0 = MLA ? 0 : q0 + 64 * jt0;
;     const int qlo = q0 + wid * 32, qm = qlo + r32 - 4 * hi;
;     bf16x8 qr[NQF];
;     const size_t qrow = rowbase + qlo + r32;
;     if constexpr (MLA) {
; #pragma unroll
;         for (int d0 = 0; d0 < 8; ++d0) qr[d0] = *(const bf16x8*)(P.QN + qrow * 2048 + hh * 128 + d0 * 16 + hi * 8);
; #pragma unroll
;         for (int d0 = 0; d0 < 4; ++d0) qr[8 + d0] = *(const bf16x8*)(P.QR + qrow * 1024 + hh * 64 + d0 * 16 + hi * 8);
;     } else {
; #pragma unroll
;         for (int d0 = 0; d0 < 4; ++d0) qr[d0] = *(const bf16x8*)(P.QS + qrow * 2048 + hh * 64 + d0 * 16 + hi * 8);
;         if (tid < 128) bias_l[tid] = P.rel[(int)T5B[tid] * 32 + hh] * (1.0f / SCALE);
;     }
;     bf16x8 sk0, sv0;
;     const int sr8 = tid >> 3, ch8 = tid & 7;
;     const bf16_t* Kg; const bf16_t* Vg; const bf16_t* Rg = nullptr;
;     unsigned okA = 0, okB = 0, orp = 0, ovA = 0, ovB = 0;
;     if constexpr (MLA) {
;         Kg = P.KN + rowbase * 2048 + hh * 128; Vg = P.V + rowbase * 2048 + hh * 128; Rg = P.KR + rowbase * 64;
;         { const int rA = 4 * wid + (lane >> 4), rB = rA + 32, cp = lane & 15; okA = (unsigned)(rA * 2048 + ((cp ^ (rA & 7)) << 3)); okB = (unsigned)(rB * 2048 + ((cp ^ (rB & 7)) << 3)); }
;         { const int rr = 8 * wid + (lane >> 3), cp = lane & 7; orp = (unsigned)(rr * 64 + ((cp ^ (rr & 7)) << 3)); }
;         { const int stA = 2 * wid + (lane >> 5), stB = stA + 16; const int kl = (lane & 31) >> 2, c8 = 8 * (lane & 3);
;           const int kkA = (stA >> 2) * 8 + kl, kkB = (stB >> 2) * 8 + kl;
.LBB0_301:
	s_cmp_lt_i32 s54, 4
	s_cselect_b64 s[4:5], -1, 0
	s_and_b64 s[44:45], s[4:5], s[0:1]
	s_andn2_b64 vcc, exec, s[44:45]
	s_cbranch_vccnz .LBB0_682
	s_cmpk_gt_i32 s2, 0x3ff
	v_lshrrev_b32_e32 v1, 5, v206
	v_and_b32_e32 v198, 7, v162
	v_lshrrev_b32_e32 v200, 2, v162
	v_lshlrev_b32_e32 v147, 3, v162
	v_lshlrev_b32_e32 v199, 1, v162
	v_cmp_gt_u32_e64 s[0:1], 32, v206
	v_and_b32_e32 v151, 1, v162
	s_cbranch_scc1 .LBB0_597
	v_readfirstlane_b32 s4, v162
	s_nop 3
	s_lshr_b32 s4, s4, 6
	s_lshl_b32 s5, s4, 10
	s_add_u32 s6, s52, 0x1e000000
	s_addc_u32 s7, s53, 0
	s_add_u32 s8, s52, 0x26000000
	s_addc_u32 s9, s53, 0
	s_add_u32 s12, s52, 0x2a000000
	s_addc_u32 s13, s53, 0
	s_add_u32 s14, s52, 0x13c00000
	s_addc_u32 s15, s53, 0
	s_add_u32 s16, s52, 0x32000000
	s_addc_u32 s17, s53, 0
	s_mov_b32 s72, 0x4138aa3b
	v_mov_b32_e32 v245, 0xff800000
	v_mov_b32_e32 v248, 0
	v_and_b32_e32 v221, 15, v206
	v_lshrrev_b32_e32 v222, 4, v206
	v_lshrrev_b32_e32 v223, 1, v221
	v_xor_b32_e32 v223, v223, v222
	v_lshlrev_b32_e32 v223, 4, v223
	v_lshl_or_b32 v224, v221, 7, v223
	v_xor_b32_e32 v225, 64, v224
	v_lshrrev_b32_e32 v223, 1, v222
	v_lshlrev_b32_e32 v223, 11, v223
	v_and_b32_e32 v220, 1, v222
	v_lshl_or_b32 v223, v220, 8, v223
	v_lshrrev_b32_e32 v226, 2, v221
	v_lshl_or_b32 v223, v226, 6, v223
	v_and_b32_e32 v226, 3, v221
	v_lshl_or_b32 v223, v226, 3, v223
	v_lshlrev_b32_e32 v220, 5, v220
	v_or_b32_e32 v226, v223, v220
	v_xor_b32_e32 v220, 32, v220
	v_or_b32_e32 v227, v223, v220
	v_add_u32_e32 v224, 0x8000, v224
	v_add_u32_e32 v228, 0x6000, v224
	v_add_u32_e32 v230, 0x4000, v226
	v_add_u32_e32 v225, 0x8000, v225
	v_add_u32_e32 v229, 0x6000, v225
	v_add_u32_e32 v231, 0x4000, v227
	v_lshlrev_b32_e32 v223, 2, v222
	v_sub_u32_e32 v243, v221, v223
	v_xor_b32_e32 v246, 16, v206
	v_lshlrev_b32_e32 v246, 2, v246
	v_xor_b32_e32 v247, 32, v206
	v_lshlrev_b32_e32 v247, 2, v247
	v_lshlrev_b32_e32 v223, 4, v222
	v_lshl_or_b32 v237, v221, 12, v223
	v_add_u32_e32 v238, 0x10000, v237
	v_lshl_or_b32 v239, v221, 11, v223
	v_add_u32_e32 v240, 0x8000, v239
	v_lshlrev_b32_e32 v223, 3, v222
	v_lshl_or_b32 v241, v221, 12, v223
	v_add_u32_e32 v242, 0x10000, v241
	v_bfe_u32 v221, v162, 4, 3
	v_bitop3_b32 v221, v221, v162, 7 bitop3:0x78
	v_lshlrev_b32_e32 v221, 4, v221
	v_lshrrev_b32_e32 v222, 3, v162
	v_lshl_or_b32 v232, v222, 12, v221
	v_add_u32_e32 v233, 0x80, v232
	v_lshl_or_b32 v234, v222, 7, v221
	v_bfe_u32 v221, v206, 2, 3
	v_lshrrev_b32_e32 v222, 2, v221
	v_lshlrev_b32_e32 v222, 1, v222
	v_and_b32_e32 v223, 3, v206
	v_xor_b32_e32 v223, v223, v222
	v_lshlrev_b32_e32 v223, 4, v223
	v_lshrrev_b32_e32 v222, 5, v206
	v_lshl_or_b32 v223, v222, 6, v223
	s_lshr_b32 s36, s4, 1
	s_lshl_b32 s36, s36, 15
	s_and_b32 s37, s4, 1
	s_lshl_b32 s37, s37, 7
	s_add_i32 s36, s36, s37
	v_lshl_or_b32 v223, v221, 12, v223
	v_add_u32_e32 v235, s36, v223
	v_add_u32_e32 v236, 0x20000, v235
	s_mov_b32 s28, s2

; #define WLK(n) do { asm volatile("s_waitcnt lgkmcnt(" #n ")" ::: "memory"); SBAR(); } while (0)
; #define RDN(S, dd, off) do { const int a_ = rb + (((dd) * 32 + h16) ^ sw); KRD(S##0, a_, off); KRD(S##1, a_, 8192 + (off)); } while (0)
; #define RDR(S, ks) do { const int a_ = rr + (((((ks) * 2 + hi)) ^ (r32 & 7)) << 4); KRD(S##0, a_, 0); KRD(S##1, a_, 4096); } while (0)
; #define MM1(S, d) do { p0 = __builtin_amdgcn_mfma_f32_32x32x16_bf16(S##0, qr[d], p0, 0, 0, 0); p1 = __builtin_amdgcn_mfma_f32_32x32x16_bf16(S##1, qr[d], p1, 0, 0, 0); } while (0)
; __device__ __forceinline__ void qk_mla(f32x16& p0, f32x16& p1, int kaddr, int r32, int hi, const bf16x8* qr) {
;     const int rb = kaddr + r32 * 256, sw = (r32 & 7) << 4, h16 = hi * 16;
;     const int rr = kaddr + 16384 + r32 * 128;
;     ...
;     bf16x8 A0, A1, B0, B1;
;     RDN(A, 0, 0); RDN(B, 1, 0);
;     WLK(2); MM1(A, 0); RDN(A, 2, 0);
;     WLK(2); MM1(B, 1); RDN(B, 3, 0);
;     WLK(2); MM1(A, 2); RDN(A, 0, 128);
;     WLK(2); MM1(B, 3); RDN(B, 1, 128);
;     WLK(2); MM1(A, 4); RDN(A, 2, 128);
;     WLK(2); MM1(B, 5); RDN(B, 3, 128);
;     WLK(2); MM1(A, 6); RDR(A, 0);
;     WLK(2); MM1(B, 7); RDR(B, 1);
;     WLK(2); MM1(A, 8); RDR(A, 2);
;     WLK(2); MM1(B, 9); RDR(B, 3);
;     WLK(2); MM1(A, 10);
;     WLK(0); MM1(B, 11);
; template <bool MLA> __device__ __forceinline__ void attn_unit(const AttnP& P, int b, int hh, int qb, LAS char* lds) {
;     ...
;     for (int t = 0; t < NT; ++t) {
;         const int buf = t & 1;
;         if (t + 1 < NT) LOADT(t + 1, buf ^ 1);
;         const int kb = kbase0 + 64 * t;
;         const bool act = (kb <= qlo + 31) && (MLA || kb + 63 >= qlo - (W - 1));
;         if (act) {
;             f32x16 p0 = f32x16{}, p1 = f32x16{};
;             if constexpr (MLA) {
; #pragma unroll
;                 for (int r = 0; r < 16; ++r) { p0[r] = -m_reg; p1[r] = -m_reg; } }
;             if constexpr (MLA) { qk_mla(p0, p1, (int)(uintptr_t)K_lds + buf * KBYTES, r32, hi, qr); }
;             else { qk64(p0, p1, K_lds + buf * KBYTES, r32, hi, qr); }
.Lm16_tile:
	s_add_u32 s36, s41, 1
	s_cmp_lt_u32 s36, s40
	s_cbranch_scc0 .Lm16_noload0
	s_add_i32 s36, s5, 0xe000
	s_mov_b32 m0, s36
	s_nop 0
	global_load_lds_dwordx4 v232, s[46:47]
	s_add_i32 m0, s36, 0x2000
	s_nop 0
	global_load_lds_dwordx4 v233, s[46:47]
	s_add_i32 m0, s36, 0x4000
	s_nop 0
	global_load_lds_dwordx4 v234, s[50:51]
	s_add_i32 s36, s5, 0x4000
	s_mov_b32 m0, s36
	s_nop 0
	global_load_lds_dwordx4 v235, s[48:49]
	s_add_i32 m0, s36, 0x2000
	s_nop 0
	global_load_lds_dwordx4 v236, s[48:49]
	s_add_u32 s46, s46, 0x40000
	s_addc_u32 s47, s47, 0
	s_add_u32 s48, s48, 0x40000
	s_addc_u32 s49, s49, 0
	s_add_u32 s50, s50, 0x2000
	s_addc_u32 s51, s51, 0
.Lm16_noload0:
	s_add_u32 s36, s43, 31
	s_cmp_gt_u32 s42, s36
	s_cbranch_scc1 .Lm16_tile_end0
	ds_read_b128 v[180:183], v224 offset:0
	ds_read_b128 v[184:187], v224 offset:2048
	ds_read_b128 v[188:191], v224 offset:4096
	ds_read_b128 v[192:195], v224 offset:6144
	s_waitcnt lgkmcnt(3)
	v_mfma_f32_16x16x32_bf16 v[114:117], v[180:183], v[66:69], v[208:211]
	v_mfma_f32_16x16x32_bf16 v[118:121], v[180:183], v[90:93], v[212:215]
	ds_read_b128 v[180:183], v225 offset:0
	s_waitcnt lgkmcnt(3)
	v_mfma_f32_16x16x32_bf16 v[122:125], v[184:187], v[66:69], v[208:211]
	v_mfma_f32_16x16x32_bf16 v[126:129], v[184:187], v[90:93], v[212:215]
	ds_read_b128 v[184:187], v225 offset:2048
	s_waitcnt lgkmcnt(3)
	v_mfma_f32_16x16x32_bf16 v[130:133], v[188:191], v[66:69], v[208:211]
	v_mfma_f32_16x16x32_bf16 v[134:137], v[188:191], v[90:93], v[212:215]
	ds_read_b128 v[188:191], v225 offset:4096
	s_waitcnt lgkmcnt(3)
	v_mfma_f32_16x16x32_bf16 v[138:141], v[192:195], v[66:69], v[208:211]
	v_mfma_f32_16x16x32_bf16 v[142:145], v[192:195], v[90:93], v[212:215]
	ds_read_b128 v[192:195], v225 offset:6144
	s_waitcnt lgkmcnt(3)
	v_mfma_f32_16x16x32_bf16 v[114:117], v[180:183], v[70:73], v[114:117]
	v_mfma_f32_16x16x32_bf16 v[118:121], v[180:183], v[94:97], v[118:121]
	ds_read_b128 v[180:183], v224 offset:8192
	s_waitcnt lgkmcnt(3)
	v_mfma_f32_16x16x32_bf16 v[122:125], v[184:187], v[70:73], v[122:125]
	v_mfma_f32_16x16x32_bf16 v[126:129], v[184:187], v[94:97], v[126:129]
	ds_read_b128 v[184:187], v224 offset:10240
	s_waitcnt lgkmcnt(3)
	v_mfma_f32_16x16x32_bf16 v[130:133], v[188:191], v[70:73], v[130:133]
	v_mfma_f32_16x16x32_bf16 v[134:137], v[188:191], v[94:97], v[134:137]
	ds_read_b128 v[188:191], v224 offset:12288
	s_waitcnt lgkmcnt(3)
	v_mfma_f32_16x16x32_bf16 v[138:141], v[192:195], v[70:73], v[138:141]
	v_mfma_f32_16x16x32_bf16 v[142:145], v[192:195], v[94:97], v[142:145]
	ds_read_b128 v[192:195], v224 offset:14336
	s_waitcnt lgkmcnt(3)
	v_mfma_f32_16x16x32_bf16 v[114:117], v[180:183], v[74:77], v[114:117]
	v_mfma_f32_16x16x32_bf16 v[118:121], v[180:183], v[98:101], v[118:121]
	ds_read_b128 v[180:183], v225 offset:8192
	s_waitcnt lgkmcnt(3)
	v_mfma_f32_16x16x32_bf16 v[122:125], v[184:187], v[74:77], v[122:125]
	v_mfma_f32_16x16x32_bf16 v[126:129], v[184:187], v[98:101], v[126:129]
	ds_read_b128 v[184:187], v225 offset:10240
	s_waitcnt lgkmcnt(3)
	v_mfma_f32_16x16x32_bf16 v[130:133], v[188:191], v[74:77], v[130:133]
	v_mfma_f32_16x16x32_bf16 v[134:137], v[188:191], v[98:101], v[134:137]
	ds_read_b128 v[188:191], v225 offset:12288
	s_waitcnt lgkmcnt(3)
	v_mfma_f32_16x16x32_bf16 v[138:141], v[192:195], v[74:77], v[138:141]
	v_mfma_f32_16x16x32_bf16 v[142:145], v[192:195], v[98:101], v[142:145]
	ds_read_b128 v[192:195], v225 offset:14336
	s_waitcnt lgkmcnt(3)
	v_mfma_f32_16x16x32_bf16 v[114:117], v[180:183], v[78:81], v[114:117]
	v_mfma_f32_16x16x32_bf16 v[118:121], v[180:183], v[102:105], v[118:121]
	ds_read_b128 v[180:183], v224 offset:16384
	s_waitcnt lgkmcnt(3)
	v_mfma_f32_16x16x32_bf16 v[122:125], v[184:187], v[78:81], v[122:125]
	v_mfma_f32_16x16x32_bf16 v[126:129], v[184:187], v[102:105], v[126:129]
	ds_read_b128 v[184:187], v224 offset:18432
	s_waitcnt lgkmcnt(3)
	v_mfma_f32_16x16x32_bf16 v[130:133], v[188:191], v[78:81], v[130:133]
	v_mfma_f32_16x16x32_bf16 v[134:137], v[188:191], v[102:105], v[134:137]
	ds_read_b128 v[188:191], v224 offset:20480
	s_waitcnt lgkmcnt(3)
	v_mfma_f32_16x16x32_bf16 v[138:141], v[192:195], v[78:81], v[138:141]
	v_mfma_f32_16x16x32_bf16 v[142:145], v[192:195], v[102:105], v[142:145]
	ds_read_b128 v[192:195], v224 offset:22528
	s_waitcnt lgkmcnt(3)
	v_mfma_f32_16x16x32_bf16 v[114:117], v[180:183], v[82:85], v[114:117]
	v_mfma_f32_16x16x32_bf16 v[118:121], v[180:183], v[106:109], v[118:121]
	ds_read_b128 v[180:183], v225 offset:16384
	s_waitcnt lgkmcnt(3)
	v_mfma_f32_16x16x32_bf16 v[122:125], v[184:187], v[82:85], v[122:125]
	v_mfma_f32_16x16x32_bf16 v[126:129], v[184:187], v[106:109], v[126:129]
	ds_read_b128 v[184:187], v225 offset:18432
	s_waitcnt lgkmcnt(3)
	v_mfma_f32_16x16x32_bf16 v[130:133], v[188:191], v[82:85], v[130:133]
	v_mfma_f32_16x16x32_bf16 v[134:137], v[188:191], v[106:109], v[134:137]
	ds_read_b128 v[188:191], v225 offset:20480
	s_waitcnt lgkmcnt(3)
	v_mfma_f32_16x16x32_bf16 v[138:141], v[192:195], v[82:85], v[138:141]
	v_mfma_f32_16x16x32_bf16 v[142:145], v[192:195], v[106:109], v[142:145]
	ds_read_b128 v[192:195], v225 offset:22528
	s_waitcnt lgkmcnt(3)
	v_mfma_f32_16x16x32_bf16 v[114:117], v[180:183], v[86:89], v[114:117]
	v_mfma_f32_16x16x32_bf16 v[118:121], v[180:183], v[110:113], v[118:121]
	s_waitcnt lgkmcnt(2)
	v_mfma_f32_16x16x32_bf16 v[122:125], v[184:187], v[86:89], v[122:125]
	v_mfma_f32_16x16x32_bf16 v[126:129], v[184:187], v[110:113], v[126:129]
	s_waitcnt lgkmcnt(1)
	v_mfma_f32_16x16x32_bf16 v[130:133], v[188:191], v[86:89], v[130:133]
	v_mfma_f32_16x16x32_bf16 v[134:137], v[188:191], v[110:113], v[134:137]
	s_waitcnt lgkmcnt(0)
	v_mfma_f32_16x16x32_bf16 v[138:141], v[192:195], v[86:89], v[138:141]
	v_mfma_f32_16x16x32_bf16 v[142:145], v[192:195], v[110:113], v[142:145]
	s_nop 7
	s_add_u32 s36, s42, 63
	s_cmp_gt_u32 s36, s43
	s_cbranch_scc0 .Lm16_nomask0
; __device__ __forceinline__ void mask_tile(f32x16& p0, f32x16& p1, int dq, unsigned W) {
;     const float NEG = -__builtin_inff();
; #pragma unroll
;     for (int r = 0; r < 16; ++r) { const int c = (r & 3) + 8 * (r >> 2);
;         if ((unsigned)(dq - c) >= W) p0[r] = NEG;
;         if ((unsigned)(dq - c - 32) >= W) p1[r] = NEG; }
; }
; __device__ __forceinline__ void partialSM_pre(f32x16& p0, f32x16& p1, float& m_reg, float& alpha) {
;     ...
;     if (__builtin_expect(__all(pmax <= THR2), 1)) { alpha = 1.f; }
;     else { const float d = fmaxf(pmax, 0.f); m_reg += d; alpha = __builtin_amdgcn_exp2f(-d);
; #pragma unroll
;         for (int r = 0; r < 16; ++r) { p0[r] -= d; p1[r] -= d; } }
; #pragma unroll
;     for (int r = 0; r < 16; ++r) p0[r] = __builtin_amdgcn_exp2f(p0[r]);
; }
; __device__ __forceinline__ void finishSM(f32x16& p0, f32x16& p1, float alpha, float& l_reg, bf16x8& pa0, bf16x8& pa1, bf16x8& pa2, bf16x8& pa3) {
; #pragma unroll
;     for (int r = 0; r < 16; ++r) p1[r] = __builtin_amdgcn_exp2f(p1[r]);
;     float ps = 0;
; #pragma unroll
;     for (int r = 0; r < 16; ++r) ps += p0[r];
; #pragma unroll
;     for (int r = 0; r < 16; ++r) ps += p1[r];
;     { auto rr = __builtin_amdgcn_permlane32_swap(__float_as_uint(ps), __float_as_uint(ps), false, false);
;       ps = __uint_as_float(rr[0]) + __uint_as_float(rr[1]); }
;     l_reg = l_reg * alpha + ps;
;     ...
;     PK4(p0, 0, pa0); PK4(p0, 8, pa1); PK4(p1, 0, pa2); PK4(p1, 8, pa3);
	s_sub_u32 s36, s43, s42
	v_add_u32_e32 v244, s36, v243
	v_cmp_gt_i32_e32 vcc, 0, v244
	s_nop 1
	v_cndmask_b32_e32 v114, v114, v245, vcc
	v_cmp_gt_i32_e32 vcc, 1, v244
	s_nop 1
	v_cndmask_b32_e32 v115, v115, v245, vcc
	v_cmp_gt_i32_e32 vcc, 2, v244
	s_nop 1
	v_cndmask_b32_e32 v116, v116, v245, vcc
	v_cmp_gt_i32_e32 vcc, 3, v244
	s_nop 1
	v_cndmask_b32_e32 v117, v117, v245, vcc
	v_cmp_gt_i32_e32 vcc, -16, v244
	s_nop 1
	v_cndmask_b32_e32 v118, v118, v245, vcc
	v_cmp_gt_i32_e32 vcc, -15, v244
	s_nop 1
	v_cndmask_b32_e32 v119, v119, v245, vcc
	v_cmp_gt_i32_e32 vcc, -14, v244
	s_nop 1
	v_cndmask_b32_e32 v120, v120, v245, vcc
	v_cmp_gt_i32_e32 vcc, -13, v244
	s_nop 1
	v_cndmask_b32_e32 v121, v121, v245, vcc
	v_cmp_gt_i32_e32 vcc, 16, v244
	s_nop 1
	v_cndmask_b32_e32 v122, v122, v245, vcc
	v_cmp_gt_i32_e32 vcc, 17, v244
	s_nop 1
	v_cndmask_b32_e32 v123, v123, v245, vcc
	v_cmp_gt_i32_e32 vcc, 18, v244
	s_nop 1
	v_cndmask_b32_e32 v124, v124, v245, vcc
	v_cmp_gt_i32_e32 vcc, 19, v244
	s_nop 1
	v_cndmask_b32_e32 v125, v125, v245, vcc
	v_cmp_gt_i32_e32 vcc, 0, v244
	s_nop 1
	v_cndmask_b32_e32 v126, v126, v245, vcc
	v_cmp_gt_i32_e32 vcc, 1, v244
	s_nop 1
	v_cndmask_b32_e32 v127, v127, v245, vcc
	v_cmp_gt_i32_e32 vcc, 2, v244
	s_nop 1
	v_cndmask_b32_e32 v128, v128, v245, vcc
	v_cmp_gt_i32_e32 vcc, 3, v244
	s_nop 1
	v_cndmask_b32_e32 v129, v129, v245, vcc
	v_cmp_gt_i32_e32 vcc, 32, v244
	s_nop 1
	v_cndmask_b32_e32 v130, v130, v245, vcc
	v_cmp_gt_i32_e32 vcc, 33, v244
	s_nop 1
	v_cndmask_b32_e32 v131, v131, v245, vcc
	v_cmp_gt_i32_e32 vcc, 34, v244
	s_nop 1
	v_cndmask_b32_e32 v132, v132, v245, vcc
	v_cmp_gt_i32_e32 vcc, 35, v244
	s_nop 1
	v_cndmask_b32_e32 v133, v133, v245, vcc
	v_cmp_gt_i32_e32 vcc, 16, v244
	s_nop 1
	v_cndmask_b32_e32 v134, v134, v245, vcc
	v_cmp_gt_i32_e32 vcc, 17, v244
	s_nop 1
	v_cndmask_b32_e32 v135, v135, v245, vcc
	v_cmp_gt_i32_e32 vcc, 18, v244
	s_nop 1
	v_cndmask_b32_e32 v136, v136, v245, vcc
	v_cmp_gt_i32_e32 vcc, 19, v244
	s_nop 1
	v_cndmask_b32_e32 v137, v137, v245, vcc
	v_cmp_gt_i32_e32 vcc, 48, v244
	s_nop 1
	v_cndmask_b32_e32 v138, v138, v245, vcc
	v_cmp_gt_i32_e32 vcc, 49, v244
	s_nop 1
	v_cndmask_b32_e32 v139, v139, v245, vcc
	v_cmp_gt_i32_e32 vcc, 50, v244
	s_nop 1
	v_cndmask_b32_e32 v140, v140, v245, vcc
	v_cmp_gt_i32_e32 vcc, 51, v244
	s_nop 1
	v_cndmask_b32_e32 v141, v141, v245, vcc
	v_cmp_gt_i32_e32 vcc, 32, v244
	s_nop 1
	v_cndmask_b32_e32 v142, v142, v245, vcc
	v_cmp_gt_i32_e32 vcc, 33, v244
	s_nop 1
	v_cndmask_b32_e32 v143, v143, v245, vcc
	v_cmp_gt_i32_e32 vcc, 34, v244
	s_nop 1
	v_cndmask_b32_e32 v144, v144, v245, vcc
	v_cmp_gt_i32_e32 vcc, 35, v244
	s_nop 1
	v_cndmask_b32_e32 v145, v145, v245, vcc
.Lm16_nomask0:
	v_exp_f32_e32 v114, v114
	v_exp_f32_e32 v115, v115
	v_exp_f32_e32 v116, v116
	v_exp_f32_e32 v117, v117
	v_exp_f32_e32 v118, v118
	v_exp_f32_e32 v119, v119
	v_exp_f32_e32 v120, v120
	v_exp_f32_e32 v121, v121
	v_exp_f32_e32 v122, v122
	v_exp_f32_e32 v123, v123
	v_exp_f32_e32 v124, v124
	v_exp_f32_e32 v125, v125
	v_exp_f32_e32 v126, v126
	v_exp_f32_e32 v127, v127
	v_exp_f32_e32 v128, v128
	v_exp_f32_e32 v129, v129
	v_exp_f32_e32 v130, v130
	v_exp_f32_e32 v131, v131
	v_exp_f32_e32 v132, v132
	v_exp_f32_e32 v133, v133
	v_exp_f32_e32 v134, v134
	v_exp_f32_e32 v135, v135
	v_exp_f32_e32 v136, v136
	v_exp_f32_e32 v137, v137
	v_exp_f32_e32 v138, v138
	v_exp_f32_e32 v139, v139
	v_exp_f32_e32 v140, v140
	v_exp_f32_e32 v141, v141
	v_exp_f32_e32 v142, v142
	v_exp_f32_e32 v143, v143
	v_exp_f32_e32 v144, v144
	v_exp_f32_e32 v145, v145
	v_cvt_pk_bf16_f32 v164, v114, v115
	v_cvt_pk_bf16_f32 v165, v116, v117
	v_cvt_pk_bf16_f32 v166, v122, v123
	v_cvt_pk_bf16_f32 v167, v124, v125
	v_cvt_pk_bf16_f32 v168, v130, v131
	v_cvt_pk_bf16_f32 v169, v132, v133
	v_cvt_pk_bf16_f32 v170, v138, v139
	v_cvt_pk_bf16_f32 v171, v140, v141
	v_cvt_pk_bf16_f32 v172, v118, v119
	v_cvt_pk_bf16_f32 v173, v120, v121
	v_cvt_pk_bf16_f32 v174, v126, v127
	v_cvt_pk_bf16_f32 v175, v128, v129
	v_cvt_pk_bf16_f32 v176, v134, v135
	v_cvt_pk_bf16_f32 v177, v136, v137
	v_cvt_pk_bf16_f32 v178, v142, v143
	v_cvt_pk_bf16_f32 v179, v144, v145
	v_or3_b32 v220, v164, v165, v166
	v_or3_b32 v221, v167, v168, v169
	v_or3_b32 v222, v170, v171, v172
	v_or3_b32 v223, v173, v174, v175
	v_or3_b32 v158, v176, v177, v178
	v_or3_b32 v220, v220, v221, v222
	v_or3_b32 v223, v223, v158, v179
	v_or_b32_e32 v220, v220, v223
	v_and_b32_e32 v220, 0x40004000, v220
	v_cmp_eq_u32_e32 vcc, 0, v220
	s_cmp_eq_u64 vcc, exec
	s_cbranch_scc1 .Lm16_pv0
; #define WLK(n) do { asm volatile("s_waitcnt lgkmcnt(" #n ")" ::: "memory"); SBAR(); } while (0)
; #define RDN(S, dd, off) do { const int a_ = rb + (((dd) * 32 + h16) ^ sw); KRD(S##0, a_, off); KRD(S##1, a_, 8192 + (off)); } while (0)
; #define RDR(S, ks) do { const int a_ = rr + (((((ks) * 2 + hi)) ^ (r32 & 7)) << 4); KRD(S##0, a_, 0); KRD(S##1, a_, 4096); } while (0)
; #define MM1(S, d) do { p0 = __builtin_amdgcn_mfma_f32_32x32x16_bf16(S##0, qr[d], p0, 0, 0, 0); p1 = __builtin_amdgcn_mfma_f32_32x32x16_bf16(S##1, qr[d], p1, 0, 0, 0); } while (0)
; __device__ __forceinline__ void qk_mla(f32x16& p0, f32x16& p1, int kaddr, int r32, int hi, const bf16x8* qr) {
;     const int rb = kaddr + r32 * 256, sw = (r32 & 7) << 4, h16 = hi * 16;
;     const int rr = kaddr + 16384 + r32 * 128;
;     ...
;     bf16x8 A0, A1, B0, B1;
;     RDN(A, 0, 0); RDN(B, 1, 0);
;     WLK(2); MM1(A, 0); RDN(A, 2, 0);
;     WLK(2); MM1(B, 1); RDN(B, 3, 0);
;     WLK(2); MM1(A, 2); RDN(A, 0, 128);
;     WLK(2); MM1(B, 3); RDN(B, 1, 128);
;     WLK(2); MM1(A, 4); RDN(A, 2, 128);
;     WLK(2); MM1(B, 5); RDN(B, 3, 128);
;     WLK(2); MM1(A, 6); RDR(A, 0);
;     WLK(2); MM1(B, 7); RDR(B, 1);
;     WLK(2); MM1(A, 8); RDR(A, 2);
;     WLK(2); MM1(B, 9); RDR(B, 3);
;     WLK(2); MM1(A, 10);
;     WLK(0); MM1(B, 11);
	ds_read_b128 v[180:183], v224 offset:0
	ds_read_b128 v[184:187], v224 offset:2048
	ds_read_b128 v[188:191], v224 offset:4096
	ds_read_b128 v[192:195], v224 offset:6144
	s_waitcnt lgkmcnt(3)
	v_mfma_f32_16x16x32_bf16 v[114:117], v[180:183], v[66:69], v[208:211]
	v_mfma_f32_16x16x32_bf16 v[118:121], v[180:183], v[90:93], v[212:215]
	ds_read_b128 v[180:183], v225 offset:0
	s_waitcnt lgkmcnt(3)
	v_mfma_f32_16x16x32_bf16 v[122:125], v[184:187], v[66:69], v[208:211]
	v_mfma_f32_16x16x32_bf16 v[126:129], v[184:187], v[90:93], v[212:215]
	ds_read_b128 v[184:187], v225 offset:2048
	s_waitcnt lgkmcnt(3)
	v_mfma_f32_16x16x32_bf16 v[130:133], v[188:191], v[66:69], v[208:211]
	v_mfma_f32_16x16x32_bf16 v[134:137], v[188:191], v[90:93], v[212:215]
	ds_read_b128 v[188:191], v225 offset:4096
	s_waitcnt lgkmcnt(3)
	v_mfma_f32_16x16x32_bf16 v[138:141], v[192:195], v[66:69], v[208:211]
	v_mfma_f32_16x16x32_bf16 v[142:145], v[192:195], v[90:93], v[212:215]
	ds_read_b128 v[192:195], v225 offset:6144
	s_waitcnt lgkmcnt(3)
	v_mfma_f32_16x16x32_bf16 v[114:117], v[180:183], v[70:73], v[114:117]
	v_mfma_f32_16x16x32_bf16 v[118:121], v[180:183], v[94:97], v[118:121]
	ds_read_b128 v[180:183], v224 offset:8192
	s_waitcnt lgkmcnt(3)
	v_mfma_f32_16x16x32_bf16 v[122:125], v[184:187], v[70:73], v[122:125]
	v_mfma_f32_16x16x32_bf16 v[126:129], v[184:187], v[94:97], v[126:129]
	ds_read_b128 v[184:187], v224 offset:10240
	s_waitcnt lgkmcnt(3)
	v_mfma_f32_16x16x32_bf16 v[130:133], v[188:191], v[70:73], v[130:133]
	v_mfma_f32_16x16x32_bf16 v[134:137], v[188:191], v[94:97], v[134:137]
	ds_read_b128 v[188:191], v224 offset:12288
	s_waitcnt lgkmcnt(3)
	v_mfma_f32_16x16x32_bf16 v[138:141], v[192:195], v[70:73], v[138:141]
	v_mfma_f32_16x16x32_bf16 v[142:145], v[192:195], v[94:97], v[142:145]
	ds_read_b128 v[192:195], v224 offset:14336
	s_waitcnt lgkmcnt(3)
	v_mfma_f32_16x16x32_bf16 v[114:117], v[180:183], v[74:77], v[114:117]
	v_mfma_f32_16x16x32_bf16 v[118:121], v[180:183], v[98:101], v[118:121]
	ds_read_b128 v[180:183], v225 offset:8192
	s_waitcnt lgkmcnt(3)
	v_mfma_f32_16x16x32_bf16 v[122:125], v[184:187], v[74:77], v[122:125]
	v_mfma_f32_16x16x32_bf16 v[126:129], v[184:187], v[98:101], v[126:129]
	ds_read_b128 v[184:187], v225 offset:10240
	s_waitcnt lgkmcnt(3)
	v_mfma_f32_16x16x32_bf16 v[130:133], v[188:191], v[74:77], v[130:133]
	v_mfma_f32_16x16x32_bf16 v[134:137], v[188:191], v[98:101], v[134:137]
	ds_read_b128 v[188:191], v225 offset:12288
	s_waitcnt lgkmcnt(3)
	v_mfma_f32_16x16x32_bf16 v[138:141], v[192:195], v[74:77], v[138:141]
	v_mfma_f32_16x16x32_bf16 v[142:145], v[192:195], v[98:101], v[142:145]
	ds_read_b128 v[192:195], v225 offset:14336
	s_waitcnt lgkmcnt(3)
	v_mfma_f32_16x16x32_bf16 v[114:117], v[180:183], v[78:81], v[114:117]
	v_mfma_f32_16x16x32_bf16 v[118:121], v[180:183], v[102:105], v[118:121]
	ds_read_b128 v[180:183], v224 offset:16384
	s_waitcnt lgkmcnt(3)
	v_mfma_f32_16x16x32_bf16 v[122:125], v[184:187], v[78:81], v[122:125]
	v_mfma_f32_16x16x32_bf16 v[126:129], v[184:187], v[102:105], v[126:129]
	ds_read_b128 v[184:187], v224 offset:18432
	s_waitcnt lgkmcnt(3)
	v_mfma_f32_16x16x32_bf16 v[130:133], v[188:191], v[78:81], v[130:133]
	v_mfma_f32_16x16x32_bf16 v[134:137], v[188:191], v[102:105], v[134:137]
	ds_read_b128 v[188:191], v224 offset:20480
	s_waitcnt lgkmcnt(3)
	v_mfma_f32_16x16x32_bf16 v[138:141], v[192:195], v[78:81], v[138:141]
	v_mfma_f32_16x16x32_bf16 v[142:145], v[192:195], v[102:105], v[142:145]
	ds_read_b128 v[192:195], v224 offset:22528
	s_waitcnt lgkmcnt(3)
	v_mfma_f32_16x16x32_bf16 v[114:117], v[180:183], v[82:85], v[114:117]
	v_mfma_f32_16x16x32_bf16 v[118:121], v[180:183], v[106:109], v[118:121]
	ds_read_b128 v[180:183], v225 offset:16384
	s_waitcnt lgkmcnt(3)
	v_mfma_f32_16x16x32_bf16 v[122:125], v[184:187], v[82:85], v[122:125]
	v_mfma_f32_16x16x32_bf16 v[126:129], v[184:187], v[106:109], v[126:129]
	ds_read_b128 v[184:187], v225 offset:18432
	s_waitcnt lgkmcnt(3)
	v_mfma_f32_16x16x32_bf16 v[130:133], v[188:191], v[82:85], v[130:133]
	v_mfma_f32_16x16x32_bf16 v[134:137], v[188:191], v[106:109], v[134:137]
	ds_read_b128 v[188:191], v225 offset:20480
	s_waitcnt lgkmcnt(3)
	v_mfma_f32_16x16x32_bf16 v[138:141], v[192:195], v[82:85], v[138:141]
	v_mfma_f32_16x16x32_bf16 v[142:145], v[192:195], v[106:109], v[142:145]
	ds_read_b128 v[192:195], v225 offset:22528
	s_waitcnt lgkmcnt(3)
	v_mfma_f32_16x16x32_bf16 v[114:117], v[180:183], v[86:89], v[114:117]
	v_mfma_f32_16x16x32_bf16 v[118:121], v[180:183], v[110:113], v[118:121]
	s_waitcnt lgkmcnt(2)
	v_mfma_f32_16x16x32_bf16 v[122:125], v[184:187], v[86:89], v[122:125]
	v_mfma_f32_16x16x32_bf16 v[126:129], v[184:187], v[110:113], v[126:129]
	s_waitcnt lgkmcnt(1)
	v_mfma_f32_16x16x32_bf16 v[130:133], v[188:191], v[86:89], v[130:133]
	v_mfma_f32_16x16x32_bf16 v[134:137], v[188:191], v[110:113], v[134:137]
	s_waitcnt lgkmcnt(0)
	v_mfma_f32_16x16x32_bf16 v[138:141], v[192:195], v[86:89], v[138:141]
	v_mfma_f32_16x16x32_bf16 v[142:145], v[192:195], v[110:113], v[142:145]
	s_nop 7
	s_add_u32 s36, s42, 63
	s_cmp_gt_u32 s36, s43
	s_cbranch_scc0 .Lm16_nomask_s0
; __device__ __forceinline__ void mask_tile(f32x16& p0, f32x16& p1, int dq, unsigned W) {
;     const float NEG = -__builtin_inff();
; #pragma unroll
;     for (int r = 0; r < 16; ++r) { const int c = (r & 3) + 8 * (r >> 2);
;         if ((unsigned)(dq - c) >= W) p0[r] = NEG;
;         if ((unsigned)(dq - c - 32) >= W) p1[r] = NEG; }
; }
	s_sub_u32 s36, s43, s42
	v_add_u32_e32 v244, s36, v243
	v_cmp_gt_i32_e32 vcc, 0, v244
	s_nop 1
	v_cndmask_b32_e32 v114, v114, v245, vcc
	v_cmp_gt_i32_e32 vcc, 1, v244
	s_nop 1
	v_cndmask_b32_e32 v115, v115, v245, vcc
	v_cmp_gt_i32_e32 vcc, 2, v244
	s_nop 1
	v_cndmask_b32_e32 v116, v116, v245, vcc
	v_cmp_gt_i32_e32 vcc, 3, v244
	s_nop 1
	v_cndmask_b32_e32 v117, v117, v245, vcc
	v_cmp_gt_i32_e32 vcc, -16, v244
	s_nop 1
	v_cndmask_b32_e32 v118, v118, v245, vcc
	v_cmp_gt_i32_e32 vcc, -15, v244
	s_nop 1
	v_cndmask_b32_e32 v119, v119, v245, vcc
	v_cmp_gt_i32_e32 vcc, -14, v244
	s_nop 1
	v_cndmask_b32_e32 v120, v120, v245, vcc
	v_cmp_gt_i32_e32 vcc, -13, v244
	s_nop 1
	v_cndmask_b32_e32 v121, v121, v245, vcc
	v_cmp_gt_i32_e32 vcc, 16, v244
	s_nop 1
	v_cndmask_b32_e32 v122, v122, v245, vcc
	v_cmp_gt_i32_e32 vcc, 17, v244
	s_nop 1
	v_cndmask_b32_e32 v123, v123, v245, vcc
	v_cmp_gt_i32_e32 vcc, 18, v244
	s_nop 1
	v_cndmask_b32_e32 v124, v124, v245, vcc
	v_cmp_gt_i32_e32 vcc, 19, v244
	s_nop 1
	v_cndmask_b32_e32 v125, v125, v245, vcc
	v_cmp_gt_i32_e32 vcc, 0, v244
	s_nop 1
	v_cndmask_b32_e32 v126, v126, v245, vcc
	v_cmp_gt_i32_e32 vcc, 1, v244
	s_nop 1
	v_cndmask_b32_e32 v127, v127, v245, vcc
	v_cmp_gt_i32_e32 vcc, 2, v244
	s_nop 1
	v_cndmask_b32_e32 v128, v128, v245, vcc
	v_cmp_gt_i32_e32 vcc, 3, v244
	s_nop 1
	v_cndmask_b32_e32 v129, v129, v245, vcc
	v_cmp_gt_i32_e32 vcc, 32, v244
	s_nop 1
	v_cndmask_b32_e32 v130, v130, v245, vcc
	v_cmp_gt_i32_e32 vcc, 33, v244
	s_nop 1
	v_cndmask_b32_e32 v131, v131, v245, vcc
	v_cmp_gt_i32_e32 vcc, 34, v244
	s_nop 1
	v_cndmask_b32_e32 v132, v132, v245, vcc
	v_cmp_gt_i32_e32 vcc, 35, v244
	s_nop 1
	v_cndmask_b32_e32 v133, v133, v245, vcc
	v_cmp_gt_i32_e32 vcc, 16, v244
	s_nop 1
	v_cndmask_b32_e32 v134, v134, v245, vcc
	v_cmp_gt_i32_e32 vcc, 17, v244
	s_nop 1
	v_cndmask_b32_e32 v135, v135, v245, vcc
	v_cmp_gt_i32_e32 vcc, 18, v244
	s_nop 1
	v_cndmask_b32_e32 v136, v136, v245, vcc
	v_cmp_gt_i32_e32 vcc, 19, v244
	s_nop 1
	v_cndmask_b32_e32 v137, v137, v245, vcc
	v_cmp_gt_i32_e32 vcc, 48, v244
	s_nop 1
	v_cndmask_b32_e32 v138, v138, v245, vcc
	v_cmp_gt_i32_e32 vcc, 49, v244
	s_nop 1
	v_cndmask_b32_e32 v139, v139, v245, vcc
	v_cmp_gt_i32_e32 vcc, 50, v244
	s_nop 1
	v_cndmask_b32_e32 v140, v140, v245, vcc
	v_cmp_gt_i32_e32 vcc, 51, v244
	s_nop 1
	v_cndmask_b32_e32 v141, v141, v245, vcc
	v_cmp_gt_i32_e32 vcc, 32, v244
	s_nop 1
	v_cndmask_b32_e32 v142, v142, v245, vcc
	v_cmp_gt_i32_e32 vcc, 33, v244
	s_nop 1
	v_cndmask_b32_e32 v143, v143, v245, vcc
	v_cmp_gt_i32_e32 vcc, 34, v244
	s_nop 1
	v_cndmask_b32_e32 v144, v144, v245, vcc
	v_cmp_gt_i32_e32 vcc, 35, v244
	s_nop 1
	v_cndmask_b32_e32 v145, v145, v245, vcc

; #define PV_RD(S, d0) do { constexpr int b_ = (d0) * 512; TRRD(S##l0, b_); TRRD(S##h0, b_ + KS_ / 2); TRRD(S##l1, b_ + KS_); TRRD(S##h1, b_ + KS_ + KS_ / 2); TRRD(S##l2, b_ + 2 * KS_); TRRD(S##h2, b_ + 2 * KS_ + KS_ / 2); TRRD(S##l3, b_ + 3 * KS_); TRRD(S##h3, b_ + 3 * KS_ + KS_ / 2); } while (0)
; #define WL(n) do { asm volatile("s_waitcnt lgkmcnt(" #n ")" ::: "memory"); SBAR(); } while (0)
; template <int NCB> __device__ __forceinline__ void pv_tile(f32x16* o, int vb, bf16x8 pa0, bf16x8 pa1, bf16x8 pa2, bf16x8 pa3) {
;     ...
;     constexpr int KS_ = NCB * 1024;
;     ...
;     s16x4 Al0, Al1, Al2, Al3, Ah0, Ah1, Ah2, Ah3, Bl0, Bl1, Bl2, Bl3, Bh0, Bh1, Bh2, Bh3;
;     PV_RD(A, 0); PV_RD(B, 1); WL(8); PV_MM(A, 0);
;     if constexpr (NCB == 4) { PV_RD(A, 2); WL(8); PV_MM(B, 1); PV_RD(B, 3); WL(8); PV_MM(A, 2); WL(0); PV_MM(B, 3); }
;     else { WL(0); PV_MM(B, 1); }
; template <bool MLA> __device__ __forceinline__ void attn_unit(const AttnP& P, int b, int hh, int qb, LAS char* lds) {
;     ...
;     for (int t = 0; t < NT; ++t) {
;         const int buf = t & 1;
;         if (t + 1 < NT) LOADT(t + 1, buf ^ 1);
;         const int kb = kbase0 + 64 * t;
;         const bool act = (kb <= qlo + 31) && (MLA || kb + 63 >= qlo - (W - 1));
.Lm16_pv0:
	ds_read_b64_tr_b16 v[180:181], v226 offset:0
	ds_read_b64_tr_b16 v[182:183], v226 offset:4096
	ds_read_b64_tr_b16 v[184:185], v226 offset:8192
	ds_read_b64_tr_b16 v[186:187], v226 offset:12288
	ds_read_b64_tr_b16 v[188:189], v227 offset:0
	ds_read_b64_tr_b16 v[190:191], v227 offset:4096
	ds_read_b64_tr_b16 v[192:193], v227 offset:8192
	ds_read_b64_tr_b16 v[194:195], v227 offset:12288
	s_waitcnt lgkmcnt(6)
	v_mfma_f32_16x16x32_bf16 v[2:5], v[180:183], v[164:167], v[2:5]
	v_mfma_f32_16x16x32_bf16 v[6:9], v[180:183], v[172:175], v[6:9]
	v_mfma_f32_16x16x32_bf16 v[146:149], v[154:157], v[164:167], v[146:149]
	v_mfma_f32_16x16x32_bf16 v[150:153], v[154:157], v[172:175], v[150:153]
	ds_read_b64_tr_b16 v[180:181], v226 offset:512
	ds_read_b64_tr_b16 v[182:183], v226 offset:4608
	s_waitcnt lgkmcnt(6)
	v_mfma_f32_16x16x32_bf16 v[2:5], v[184:187], v[168:171], v[2:5]
	v_mfma_f32_16x16x32_bf16 v[6:9], v[184:187], v[176:179], v[6:9]
	v_mfma_f32_16x16x32_bf16 v[146:149], v[154:157], v[168:171], v[146:149]
	v_mfma_f32_16x16x32_bf16 v[150:153], v[154:157], v[176:179], v[150:153]
	ds_read_b64_tr_b16 v[184:185], v226 offset:8704
	ds_read_b64_tr_b16 v[186:187], v226 offset:12800
	s_waitcnt lgkmcnt(6)
	v_mfma_f32_16x16x32_bf16 v[10:13], v[188:191], v[164:167], v[10:13]
	v_mfma_f32_16x16x32_bf16 v[14:17], v[188:191], v[172:175], v[14:17]
	ds_read_b64_tr_b16 v[188:189], v227 offset:512
	ds_read_b64_tr_b16 v[190:191], v227 offset:4608
	s_waitcnt lgkmcnt(6)
	v_mfma_f32_16x16x32_bf16 v[10:13], v[192:195], v[168:171], v[10:13]
	v_mfma_f32_16x16x32_bf16 v[14:17], v[192:195], v[176:179], v[14:17]
	ds_read_b64_tr_b16 v[192:193], v227 offset:8704
	ds_read_b64_tr_b16 v[194:195], v227 offset:12800
	s_waitcnt lgkmcnt(6)
	v_mfma_f32_16x16x32_bf16 v[18:21], v[180:183], v[164:167], v[18:21]
	v_mfma_f32_16x16x32_bf16 v[22:25], v[180:183], v[172:175], v[22:25]
	ds_read_b64_tr_b16 v[180:181], v226 offset:1024
	ds_read_b64_tr_b16 v[182:183], v226 offset:5120
	s_waitcnt lgkmcnt(6)
	v_mfma_f32_16x16x32_bf16 v[18:21], v[184:187], v[168:171], v[18:21]
	v_mfma_f32_16x16x32_bf16 v[22:25], v[184:187], v[176:179], v[22:25]
	ds_read_b64_tr_b16 v[184:185], v226 offset:9216
	ds_read_b64_tr_b16 v[186:187], v226 offset:13312
	s_waitcnt lgkmcnt(6)
	v_mfma_f32_16x16x32_bf16 v[26:29], v[188:191], v[164:167], v[26:29]
	v_mfma_f32_16x16x32_bf16 v[30:33], v[188:191], v[172:175], v[30:33]
	ds_read_b64_tr_b16 v[188:189], v227 offset:1024
	ds_read_b64_tr_b16 v[190:191], v227 offset:5120
	s_waitcnt lgkmcnt(6)
	v_mfma_f32_16x16x32_bf16 v[26:29], v[192:195], v[168:171], v[26:29]
	v_mfma_f32_16x16x32_bf16 v[30:33], v[192:195], v[176:179], v[30:33]
	ds_read_b64_tr_b16 v[192:193], v227 offset:9216
	ds_read_b64_tr_b16 v[194:195], v227 offset:13312
	s_waitcnt lgkmcnt(6)
	v_mfma_f32_16x16x32_bf16 v[34:37], v[180:183], v[164:167], v[34:37]
	v_mfma_f32_16x16x32_bf16 v[38:41], v[180:183], v[172:175], v[38:41]
	ds_read_b64_tr_b16 v[180:181], v226 offset:1536
	ds_read_b64_tr_b16 v[182:183], v226 offset:5632
	s_waitcnt lgkmcnt(6)
	v_mfma_f32_16x16x32_bf16 v[34:37], v[184:187], v[168:171], v[34:37]
	v_mfma_f32_16x16x32_bf16 v[38:41], v[184:187], v[176:179], v[38:41]
	ds_read_b64_tr_b16 v[184:185], v226 offset:9728
	ds_read_b64_tr_b16 v[186:187], v226 offset:13824
	s_waitcnt lgkmcnt(6)
	v_mfma_f32_16x16x32_bf16 v[42:45], v[188:191], v[164:167], v[42:45]
	v_mfma_f32_16x16x32_bf16 v[46:49], v[188:191], v[172:175], v[46:49]
	ds_read_b64_tr_b16 v[188:189], v227 offset:1536
	ds_read_b64_tr_b16 v[190:191], v227 offset:5632
	s_waitcnt lgkmcnt(6)
	v_mfma_f32_16x16x32_bf16 v[42:45], v[192:195], v[168:171], v[42:45]
	v_mfma_f32_16x16x32_bf16 v[46:49], v[192:195], v[176:179], v[46:49]
	ds_read_b64_tr_b16 v[192:193], v227 offset:9728
	ds_read_b64_tr_b16 v[194:195], v227 offset:13824
	s_waitcnt lgkmcnt(6)
	v_mfma_f32_16x16x32_bf16 v[50:53], v[180:183], v[164:167], v[50:53]
	v_mfma_f32_16x16x32_bf16 v[54:57], v[180:183], v[172:175], v[54:57]
	s_waitcnt lgkmcnt(4)
	v_mfma_f32_16x16x32_bf16 v[50:53], v[184:187], v[168:171], v[50:53]
	v_mfma_f32_16x16x32_bf16 v[54:57], v[184:187], v[176:179], v[54:57]
	s_waitcnt lgkmcnt(2)
	v_mfma_f32_16x16x32_bf16 v[58:61], v[188:191], v[164:167], v[58:61]
	v_mfma_f32_16x16x32_bf16 v[62:65], v[188:191], v[172:175], v[62:65]
	s_waitcnt lgkmcnt(0)
	v_mfma_f32_16x16x32_bf16 v[58:61], v[192:195], v[168:171], v[58:61]
	v_mfma_f32_16x16x32_bf16 v[62:65], v[192:195], v[176:179], v[62:65]
.Lm16_tile_end0:
	s_waitcnt vmcnt(0) lgkmcnt(0)
	s_barrier
	s_add_u32 s41, s41, 1
	s_add_u32 s42, s42, 64
	s_cmp_lt_u32 s41, s40
	s_cbranch_scc0 .Lm16_done
	s_add_u32 s36, s41, 1
	s_cmp_lt_u32 s36, s40
	s_cbranch_scc0 .Lm16_noload1
	s_add_i32 s36, s5, 0x8000
	s_mov_b32 m0, s36
	s_nop 0
	global_load_lds_dwordx4 v232, s[46:47]
	s_add_i32 m0, s36, 0x2000
	s_nop 0
	global_load_lds_dwordx4 v233, s[46:47]
	s_add_i32 m0, s36, 0x4000
	s_nop 0
	global_load_lds_dwordx4 v234, s[50:51]
	s_add_i32 s36, s5, 0x0
	s_mov_b32 m0, s36
	s_nop 0
	global_load_lds_dwordx4 v235, s[48:49]
	s_add_i32 m0, s36, 0x2000
	s_nop 0
	global_load_lds_dwordx4 v236, s[48:49]
	s_add_u32 s46, s46, 0x40000
	s_addc_u32 s47, s47, 0
	s_add_u32 s48, s48, 0x40000
	s_addc_u32 s49, s49, 0
	s_add_u32 s50, s50, 0x2000
	s_addc_u32 s51, s51, 0
; #define WLK(n) do { asm volatile("s_waitcnt lgkmcnt(" #n ")" ::: "memory"); SBAR(); } while (0)
; #define RDN(S, dd, off) do { const int a_ = rb + (((dd) * 32 + h16) ^ sw); KRD(S##0, a_, off); KRD(S##1, a_, 8192 + (off)); } while (0)
; #define RDR(S, ks) do { const int a_ = rr + (((((ks) * 2 + hi)) ^ (r32 & 7)) << 4); KRD(S##0, a_, 0); KRD(S##1, a_, 4096); } while (0)
; #define MM1(S, d) do { p0 = __builtin_amdgcn_mfma_f32_32x32x16_bf16(S##0, qr[d], p0, 0, 0, 0); p1 = __builtin_amdgcn_mfma_f32_32x32x16_bf16(S##1, qr[d], p1, 0, 0, 0); } while (0)
; __device__ __forceinline__ void qk_mla(f32x16& p0, f32x16& p1, int kaddr, int r32, int hi, const bf16x8* qr) {
;     const int rb = kaddr + r32 * 256, sw = (r32 & 7) << 4, h16 = hi * 16;
;     const int rr = kaddr + 16384 + r32 * 128;
;     ...
;     bf16x8 A0, A1, B0, B1;
;     RDN(A, 0, 0); RDN(B, 1, 0);
;     WLK(2); MM1(A, 0); RDN(A, 2, 0);
;     WLK(2); MM1(B, 1); RDN(B, 3, 0);
;     WLK(2); MM1(A, 2); RDN(A, 0, 128);
;     WLK(2); MM1(B, 3); RDN(B, 1, 128);
;     WLK(2); MM1(A, 4); RDN(A, 2, 128);
;     WLK(2); MM1(B, 5); RDN(B, 3, 128);
;     WLK(2); MM1(A, 6); RDR(A, 0);
;     WLK(2); MM1(B, 7); RDR(B, 1);
;     WLK(2); MM1(A, 8); RDR(A, 2);
;     WLK(2); MM1(B, 9); RDR(B, 3);
;     WLK(2); MM1(A, 10);
;     WLK(0); MM1(B, 11);
; template <bool MLA> __device__ __forceinline__ void attn_unit(const AttnP& P, int b, int hh, int qb, LAS char* lds) {
;     ...
;         const bool act = (kb <= qlo + 31) && (MLA || kb + 63 >= qlo - (W - 1));
;         if (act) {
;             f32x16 p0 = f32x16{}, p1 = f32x16{};
;             if constexpr (MLA) {
; #pragma unroll
;                 for (int r = 0; r < 16; ++r) { p0[r] = -m_reg; p1[r] = -m_reg; } }
;             if constexpr (MLA) { qk_mla(p0, p1, (int)(uintptr_t)K_lds + buf * KBYTES, r32, hi, qr); }
;             else { qk64(p0, p1, K_lds + buf * KBYTES, r32, hi, qr); }
.Lm16_noload1:
	s_add_u32 s36, s43, 31
	s_cmp_gt_u32 s42, s36
	s_cbranch_scc1 .Lm16_tile_end1
	ds_read_b128 v[180:183], v228 offset:0
	ds_read_b128 v[184:187], v228 offset:2048
	ds_read_b128 v[188:191], v228 offset:4096
	ds_read_b128 v[192:195], v228 offset:6144
	s_waitcnt lgkmcnt(3)
	v_mfma_f32_16x16x32_bf16 v[114:117], v[180:183], v[66:69], v[208:211]
	v_mfma_f32_16x16x32_bf16 v[118:121], v[180:183], v[90:93], v[212:215]
	ds_read_b128 v[180:183], v229 offset:0
	s_waitcnt lgkmcnt(3)
	v_mfma_f32_16x16x32_bf16 v[122:125], v[184:187], v[66:69], v[208:211]
	v_mfma_f32_16x16x32_bf16 v[126:129], v[184:187], v[90:93], v[212:215]
	ds_read_b128 v[184:187], v229 offset:2048
	s_waitcnt lgkmcnt(3)
	v_mfma_f32_16x16x32_bf16 v[130:133], v[188:191], v[66:69], v[208:211]
	v_mfma_f32_16x16x32_bf16 v[134:137], v[188:191], v[90:93], v[212:215]
	ds_read_b128 v[188:191], v229 offset:4096
	s_waitcnt lgkmcnt(3)
	v_mfma_f32_16x16x32_bf16 v[138:141], v[192:195], v[66:69], v[208:211]
	v_mfma_f32_16x16x32_bf16 v[142:145], v[192:195], v[90:93], v[212:215]
	ds_read_b128 v[192:195], v229 offset:6144
	s_waitcnt lgkmcnt(3)
	v_mfma_f32_16x16x32_bf16 v[114:117], v[180:183], v[70:73], v[114:117]
	v_mfma_f32_16x16x32_bf16 v[118:121], v[180:183], v[94:97], v[118:121]
	ds_read_b128 v[180:183], v228 offset:8192
	s_waitcnt lgkmcnt(3)
	v_mfma_f32_16x16x32_bf16 v[122:125], v[184:187], v[70:73], v[122:125]
	v_mfma_f32_16x16x32_bf16 v[126:129], v[184:187], v[94:97], v[126:129]
	ds_read_b128 v[184:187], v228 offset:10240
	s_waitcnt lgkmcnt(3)
	v_mfma_f32_16x16x32_bf16 v[130:133], v[188:191], v[70:73], v[130:133]
	v_mfma_f32_16x16x32_bf16 v[134:137], v[188:191], v[94:97], v[134:137]
	ds_read_b128 v[188:191], v228 offset:12288
	s_waitcnt lgkmcnt(3)
	v_mfma_f32_16x16x32_bf16 v[138:141], v[192:195], v[70:73], v[138:141]
	v_mfma_f32_16x16x32_bf16 v[142:145], v[192:195], v[94:97], v[142:145]
	ds_read_b128 v[192:195], v228 offset:14336
	s_waitcnt lgkmcnt(3)
	v_mfma_f32_16x16x32_bf16 v[114:117], v[180:183], v[74:77], v[114:117]
	v_mfma_f32_16x16x32_bf16 v[118:121], v[180:183], v[98:101], v[118:121]
	ds_read_b128 v[180:183], v229 offset:8192
	s_waitcnt lgkmcnt(3)
	v_mfma_f32_16x16x32_bf16 v[122:125], v[184:187], v[74:77], v[122:125]
	v_mfma_f32_16x16x32_bf16 v[126:129], v[184:187], v[98:101], v[126:129]
	ds_read_b128 v[184:187], v229 offset:10240
	s_waitcnt lgkmcnt(3)
	v_mfma_f32_16x16x32_bf16 v[130:133], v[188:191], v[74:77], v[130:133]
	v_mfma_f32_16x16x32_bf16 v[134:137], v[188:191], v[98:101], v[134:137]
	ds_read_b128 v[188:191], v229 offset:12288
	s_waitcnt lgkmcnt(3)
	v_mfma_f32_16x16x32_bf16 v[138:141], v[192:195], v[74:77], v[138:141]
	v_mfma_f32_16x16x32_bf16 v[142:145], v[192:195], v[98:101], v[142:145]
	ds_read_b128 v[192:195], v229 offset:14336
	s_waitcnt lgkmcnt(3)
	v_mfma_f32_16x16x32_bf16 v[114:117], v[180:183], v[78:81], v[114:117]
	v_mfma_f32_16x16x32_bf16 v[118:121], v[180:183], v[102:105], v[118:121]
	ds_read_b128 v[180:183], v228 offset:16384
	s_waitcnt lgkmcnt(3)
	v_mfma_f32_16x16x32_bf16 v[122:125], v[184:187], v[78:81], v[122:125]
	v_mfma_f32_16x16x32_bf16 v[126:129], v[184:187], v[102:105], v[126:129]
	ds_read_b128 v[184:187], v228 offset:18432
	s_waitcnt lgkmcnt(3)
	v_mfma_f32_16x16x32_bf16 v[130:133], v[188:191], v[78:81], v[130:133]
	v_mfma_f32_16x16x32_bf16 v[134:137], v[188:191], v[102:105], v[134:137]
	ds_read_b128 v[188:191], v228 offset:20480
	s_waitcnt lgkmcnt(3)
	v_mfma_f32_16x16x32_bf16 v[138:141], v[192:195], v[78:81], v[138:141]
	v_mfma_f32_16x16x32_bf16 v[142:145], v[192:195], v[102:105], v[142:145]
	ds_read_b128 v[192:195], v228 offset:22528
	s_waitcnt lgkmcnt(3)
	v_mfma_f32_16x16x32_bf16 v[114:117], v[180:183], v[82:85], v[114:117]
	v_mfma_f32_16x16x32_bf16 v[118:121], v[180:183], v[106:109], v[118:121]
	ds_read_b128 v[180:183], v229 offset:16384
	s_waitcnt lgkmcnt(3)
	v_mfma_f32_16x16x32_bf16 v[122:125], v[184:187], v[82:85], v[122:125]
	v_mfma_f32_16x16x32_bf16 v[126:129], v[184:187], v[106:109], v[126:129]
	ds_read_b128 v[184:187], v229 offset:18432
	s_waitcnt lgkmcnt(3)
	v_mfma_f32_16x16x32_bf16 v[130:133], v[188:191], v[82:85], v[130:133]
	v_mfma_f32_16x16x32_bf16 v[134:137], v[188:191], v[106:109], v[134:137]
	ds_read_b128 v[188:191], v229 offset:20480
	s_waitcnt lgkmcnt(3)
	v_mfma_f32_16x16x32_bf16 v[138:141], v[192:195], v[82:85], v[138:141]
	v_mfma_f32_16x16x32_bf16 v[142:145], v[192:195], v[106:109], v[142:145]
	ds_read_b128 v[192:195], v229 offset:22528
	s_waitcnt lgkmcnt(3)
	v_mfma_f32_16x16x32_bf16 v[114:117], v[180:183], v[86:89], v[114:117]
	v_mfma_f32_16x16x32_bf16 v[118:121], v[180:183], v[110:113], v[118:121]
	s_waitcnt lgkmcnt(2)
	v_mfma_f32_16x16x32_bf16 v[122:125], v[184:187], v[86:89], v[122:125]
	v_mfma_f32_16x16x32_bf16 v[126:129], v[184:187], v[110:113], v[126:129]
	s_waitcnt lgkmcnt(1)
	v_mfma_f32_16x16x32_bf16 v[130:133], v[188:191], v[86:89], v[130:133]
	v_mfma_f32_16x16x32_bf16 v[134:137], v[188:191], v[110:113], v[134:137]
	s_waitcnt lgkmcnt(0)
	v_mfma_f32_16x16x32_bf16 v[138:141], v[192:195], v[86:89], v[138:141]
	v_mfma_f32_16x16x32_bf16 v[142:145], v[192:195], v[110:113], v[142:145]
	s_nop 7
	s_add_u32 s36, s42, 63
	s_cmp_gt_u32 s36, s43
	s_cbranch_scc0 .Lm16_nomask1
; __device__ __forceinline__ void mask_tile(f32x16& p0, f32x16& p1, int dq, unsigned W) {
;     const float NEG = -__builtin_inff();
; #pragma unroll
;     for (int r = 0; r < 16; ++r) { const int c = (r & 3) + 8 * (r >> 2);
;         if ((unsigned)(dq - c) >= W) p0[r] = NEG;
;         if ((unsigned)(dq - c - 32) >= W) p1[r] = NEG; }
; }
	s_sub_u32 s36, s43, s42
	v_add_u32_e32 v244, s36, v243
	v_cmp_gt_i32_e32 vcc, 0, v244
	s_nop 1
	v_cndmask_b32_e32 v114, v114, v245, vcc
	v_cmp_gt_i32_e32 vcc, 1, v244
	s_nop 1
	v_cndmask_b32_e32 v115, v115, v245, vcc
	v_cmp_gt_i32_e32 vcc, 2, v244
	s_nop 1
	v_cndmask_b32_e32 v116, v116, v245, vcc
	v_cmp_gt_i32_e32 vcc, 3, v244
	s_nop 1
	v_cndmask_b32_e32 v117, v117, v245, vcc
	v_cmp_gt_i32_e32 vcc, -16, v244
	s_nop 1
	v_cndmask_b32_e32 v118, v118, v245, vcc
	v_cmp_gt_i32_e32 vcc, -15, v244
	s_nop 1
	v_cndmask_b32_e32 v119, v119, v245, vcc
	v_cmp_gt_i32_e32 vcc, -14, v244
	s_nop 1
	v_cndmask_b32_e32 v120, v120, v245, vcc
	v_cmp_gt_i32_e32 vcc, -13, v244
	s_nop 1
	v_cndmask_b32_e32 v121, v121, v245, vcc
	v_cmp_gt_i32_e32 vcc, 16, v244
	s_nop 1
	v_cndmask_b32_e32 v122, v122, v245, vcc
	v_cmp_gt_i32_e32 vcc, 17, v244
	s_nop 1
	v_cndmask_b32_e32 v123, v123, v245, vcc
	v_cmp_gt_i32_e32 vcc, 18, v244
	s_nop 1
	v_cndmask_b32_e32 v124, v124, v245, vcc
	v_cmp_gt_i32_e32 vcc, 19, v244
	s_nop 1
	v_cndmask_b32_e32 v125, v125, v245, vcc
	v_cmp_gt_i32_e32 vcc, 0, v244
	s_nop 1
	v_cndmask_b32_e32 v126, v126, v245, vcc
	v_cmp_gt_i32_e32 vcc, 1, v244
	s_nop 1
	v_cndmask_b32_e32 v127, v127, v245, vcc
	v_cmp_gt_i32_e32 vcc, 2, v244
	s_nop 1
	v_cndmask_b32_e32 v128, v128, v245, vcc
	v_cmp_gt_i32_e32 vcc, 3, v244
	s_nop 1
	v_cndmask_b32_e32 v129, v129, v245, vcc
	v_cmp_gt_i32_e32 vcc, 32, v244
	s_nop 1
	v_cndmask_b32_e32 v130, v130, v245, vcc
	v_cmp_gt_i32_e32 vcc, 33, v244
	s_nop 1
	v_cndmask_b32_e32 v131, v131, v245, vcc
	v_cmp_gt_i32_e32 vcc, 34, v244
	s_nop 1
	v_cndmask_b32_e32 v132, v132, v245, vcc
	v_cmp_gt_i32_e32 vcc, 35, v244
	s_nop 1
	v_cndmask_b32_e32 v133, v133, v245, vcc
	v_cmp_gt_i32_e32 vcc, 16, v244
	s_nop 1
	v_cndmask_b32_e32 v134, v134, v245, vcc
	v_cmp_gt_i32_e32 vcc, 17, v244
	s_nop 1
	v_cndmask_b32_e32 v135, v135, v245, vcc
	v_cmp_gt_i32_e32 vcc, 18, v244
	s_nop 1
	v_cndmask_b32_e32 v136, v136, v245, vcc
	v_cmp_gt_i32_e32 vcc, 19, v244
	s_nop 1
	v_cndmask_b32_e32 v137, v137, v245, vcc
	v_cmp_gt_i32_e32 vcc, 48, v244
	s_nop 1
	v_cndmask_b32_e32 v138, v138, v245, vcc
	v_cmp_gt_i32_e32 vcc, 49, v244
	s_nop 1
	v_cndmask_b32_e32 v139, v139, v245, vcc
	v_cmp_gt_i32_e32 vcc, 50, v244
	s_nop 1
	v_cndmask_b32_e32 v140, v140, v245, vcc
	v_cmp_gt_i32_e32 vcc, 51, v244
	s_nop 1
	v_cndmask_b32_e32 v141, v141, v245, vcc
	v_cmp_gt_i32_e32 vcc, 32, v244
	s_nop 1
	v_cndmask_b32_e32 v142, v142, v245, vcc
	v_cmp_gt_i32_e32 vcc, 33, v244
	s_nop 1
	v_cndmask_b32_e32 v143, v143, v245, vcc
	v_cmp_gt_i32_e32 vcc, 34, v244
	s_nop 1
	v_cndmask_b32_e32 v144, v144, v245, vcc
	v_cmp_gt_i32_e32 vcc, 35, v244
	s_nop 1
	v_cndmask_b32_e32 v145, v145, v245, vcc

; #define LAS __attribute__((address_space(3)))
; __device__ __forceinline__ int crow(int r, int hi) { return (r & 3) + 8 * (r >> 2) + 4 * hi; }
; __device__ __forceinline__ unsigned cvtpk(float lo, float hi) { f32x2_cv v = {lo, hi}; bf16x2_cv b = __builtin_convertvector(v, bf16x2_cv); return __builtin_bit_cast(unsigned, b); }
; template <bool MLA> __device__ __forceinline__ void attn_unit(const AttnP& P, int b, int hh, int qb, LAS char* lds) {
;     ...
;     if (hi == 0) li_l[r32] = l_reg; asm volatile("s_waitcnt lgkmcnt(0)" ::: "memory");
;     bf16_t* Ow = (MLA ? P.QN + (rowbase + qlo) * 2048 + hh * 128 : P.QS + (rowbase + qlo) * 2048 + hh * 64);
; #pragma unroll
;     for (int r = 0; r < 16; ++r) { const int orow = crow(r, hi); const float rl = __builtin_amdgcn_rcpf(li_l[orow]);
; #pragma unroll
;         for (int d0 = 0; d0 < NCB; ++d0) { const float v = o[d0][r] * rl; const float vn = __shfl_xor(v, 1);
;             if ((r32 & 1) == 0) *(unsigned*)(Ow + (size_t)orow * 2048 + d0 * 32 + r32) = cvtpk(v, vn); } }
; __global__ void __launch_bounds__(512) fwd_mega(Args a) {
;     ...
;         for (int it = vcu; it < 1024; it += G) { const int bh = it >> 5, s = it & 31;
;             att::attn_unit<true>(P, bh >> 4, bh & 15, 63 - s, (LAS char*)lds);
;             att::attn_unit<true>(P, bh >> 4, bh & 15, s, (LAS char*)lds); }
.Lm16_done:
	s_nop 7
	v_rcp_f32_e32 v216, v146
	v_rcp_f32_e32 v217, v150
	s_nop 0
	v_mul_f32_e32 v2, v2, v216
	v_mul_f32_e32 v3, v3, v216
	v_mul_f32_e32 v4, v4, v216
	v_mul_f32_e32 v5, v5, v216
	v_cvt_pk_bf16_f32 v2, v2, v3
	v_cvt_pk_bf16_f32 v3, v4, v5
	global_store_dwordx2 v241, v[2:3], s[66:67] offset:0
	v_mul_f32_e32 v6, v6, v217
	v_mul_f32_e32 v7, v7, v217
	v_mul_f32_e32 v8, v8, v217
	v_mul_f32_e32 v9, v9, v217
	v_cvt_pk_bf16_f32 v6, v6, v7
	v_cvt_pk_bf16_f32 v7, v8, v9
	global_store_dwordx2 v242, v[6:7], s[66:67] offset:0
	v_mul_f32_e32 v10, v10, v216
	v_mul_f32_e32 v11, v11, v216
	v_mul_f32_e32 v12, v12, v216
	v_mul_f32_e32 v13, v13, v216
	v_cvt_pk_bf16_f32 v10, v10, v11
	v_cvt_pk_bf16_f32 v11, v12, v13
	global_store_dwordx2 v241, v[10:11], s[66:67] offset:32
	v_mul_f32_e32 v14, v14, v217
	v_mul_f32_e32 v15, v15, v217
	v_mul_f32_e32 v16, v16, v217
	v_mul_f32_e32 v17, v17, v217
	v_cvt_pk_bf16_f32 v14, v14, v15
	v_cvt_pk_bf16_f32 v15, v16, v17
	global_store_dwordx2 v242, v[14:15], s[66:67] offset:32
	v_mul_f32_e32 v18, v18, v216
	v_mul_f32_e32 v19, v19, v216
	v_mul_f32_e32 v20, v20, v216
	v_mul_f32_e32 v21, v21, v216
	v_cvt_pk_bf16_f32 v18, v18, v19
	v_cvt_pk_bf16_f32 v19, v20, v21
	global_store_dwordx2 v241, v[18:19], s[66:67] offset:64
	v_mul_f32_e32 v22, v22, v217
	v_mul_f32_e32 v23, v23, v217
	v_mul_f32_e32 v24, v24, v217
	v_mul_f32_e32 v25, v25, v217
	v_cvt_pk_bf16_f32 v22, v22, v23
	v_cvt_pk_bf16_f32 v23, v24, v25
	global_store_dwordx2 v242, v[22:23], s[66:67] offset:64
	v_mul_f32_e32 v26, v26, v216
	v_mul_f32_e32 v27, v27, v216
	v_mul_f32_e32 v28, v28, v216
	v_mul_f32_e32 v29, v29, v216
	v_cvt_pk_bf16_f32 v26, v26, v27
	v_cvt_pk_bf16_f32 v27, v28, v29
	global_store_dwordx2 v241, v[26:27], s[66:67] offset:96
	v_mul_f32_e32 v30, v30, v217
	v_mul_f32_e32 v31, v31, v217
	v_mul_f32_e32 v32, v32, v217
	v_mul_f32_e32 v33, v33, v217
	v_cvt_pk_bf16_f32 v30, v30, v31
	v_cvt_pk_bf16_f32 v31, v32, v33
	global_store_dwordx2 v242, v[30:31], s[66:67] offset:96
	v_mul_f32_e32 v34, v34, v216
	v_mul_f32_e32 v35, v35, v216
	v_mul_f32_e32 v36, v36, v216
	v_mul_f32_e32 v37, v37, v216
	v_cvt_pk_bf16_f32 v34, v34, v35
	v_cvt_pk_bf16_f32 v35, v36, v37
	global_store_dwordx2 v241, v[34:35], s[66:67] offset:128
	v_mul_f32_e32 v38, v38, v217
	v_mul_f32_e32 v39, v39, v217
	v_mul_f32_e32 v40, v40, v217
	v_mul_f32_e32 v41, v41, v217
	v_cvt_pk_bf16_f32 v38, v38, v39
	v_cvt_pk_bf16_f32 v39, v40, v41
	global_store_dwordx2 v242, v[38:39], s[66:67] offset:128
	v_mul_f32_e32 v42, v42, v216
	v_mul_f32_e32 v43, v43, v216
	v_mul_f32_e32 v44, v44, v216
	v_mul_f32_e32 v45, v45, v216
	v_cvt_pk_bf16_f32 v42, v42, v43
	v_cvt_pk_bf16_f32 v43, v44, v45
	global_store_dwordx2 v241, v[42:43], s[66:67] offset:160
	v_mul_f32_e32 v46, v46, v217
	v_mul_f32_e32 v47, v47, v217
	v_mul_f32_e32 v48, v48, v217
	v_mul_f32_e32 v49, v49, v217
	v_cvt_pk_bf16_f32 v46, v46, v47
	v_cvt_pk_bf16_f32 v47, v48, v49
	global_store_dwordx2 v242, v[46:47], s[66:67] offset:160
	v_mul_f32_e32 v50, v50, v216
	v_mul_f32_e32 v51, v51, v216
	v_mul_f32_e32 v52, v52, v216
	v_mul_f32_e32 v53, v53, v216
	v_cvt_pk_bf16_f32 v50, v50, v51
	v_cvt_pk_bf16_f32 v51, v52, v53
	global_store_dwordx2 v241, v[50:51], s[66:67] offset:192
	v_mul_f32_e32 v54, v54, v217
	v_mul_f32_e32 v55, v55, v217
	v_mul_f32_e32 v56, v56, v217
	v_mul_f32_e32 v57, v57, v217
	v_cvt_pk_bf16_f32 v54, v54, v55
	v_cvt_pk_bf16_f32 v55, v56, v57
	global_store_dwordx2 v242, v[54:55], s[66:67] offset:192
	v_mul_f32_e32 v58, v58, v216
	v_mul_f32_e32 v59, v59, v216
	v_mul_f32_e32 v60, v60, v216
	v_mul_f32_e32 v61, v61, v216
	v_cvt_pk_bf16_f32 v58, v58, v59
	v_cvt_pk_bf16_f32 v59, v60, v61
	global_store_dwordx2 v241, v[58:59], s[66:67] offset:224
	v_mul_f32_e32 v62, v62, v217
	v_mul_f32_e32 v63, v63, v217
	v_mul_f32_e32 v64, v64, v217
	v_mul_f32_e32 v65, v65, v217
	v_cvt_pk_bf16_f32 v62, v62, v63
	v_cvt_pk_bf16_f32 v63, v64, v65
	global_store_dwordx2 v242, v[62:63], s[66:67] offset:224
	s_add_u32 s29, s29, 1
	s_cmp_lt_u32 s29, 2
	s_cbranch_scc1 .Lm16_unit
	s_add_u32 s28, s28, s3
	s_cmp_lt_u32 s28, 0x400
	s_cbranch_scc1 .Lm16_item
	s_waitcnt vmcnt(0) lgkmcnt(0)
